# barrier hardening: first-round per-XCC census kept in its own words, arrival counters start at round 2 (no timing change intended)
# baseline (speedup 1.0000x reference)
; __global__ void __launch_bounds__(NT) fwd_kernel(Params P) {
;     ...
;   for (int ph = P.ph_lo; ph < P.ph_hi; ++ph) {
;     if (ph > P.ph_lo) grid.sync();
.LBB0_4:
	s_cmp_le_i32 s76, s66
	s_cbranch_scc1 .LBB0_16
	s_waitcnt vmcnt(0)
	s_barrier
	s_mov_b64 s[0:1], exec
	v_readlane_b32 s4, v254, 13
	v_readlane_b32 s5, v254, 14
	s_and_b64 s[4:5], s[0:1], s[4:5]
	s_mov_b64 exec, s[4:5]
	s_cbranch_execz .Lxb_join
	v_readlane_b32 s4, v254, 59
	v_readlane_b32 s5, v254, 60
	s_getreg_b32 s6, hwreg(HW_REG_XCC_ID, 0, 4)
	s_lshl_b32 s6, s6, 2
	s_add_i32 s100, s100, 1
	v_mov_b32_e32 v0, s6
	v_mov_b32_e32 v1, 1
	s_nop 4
	s_cmp_lg_u32 s98, 0
	s_cbranch_scc1 .Lxb_fast
	buffer_wbl2 sc1
	s_waitcnt vmcnt(0)
	global_atomic_add v2, v0, v1, s[4:5] offset:192 sc0
	s_waitcnt vmcnt(0)
	v_readfirstlane_b32 s9, v2
	s_cmp_lg_u32 s9, 0
	s_cbranch_scc1 .Lxb_c1
	global_atomic_add v2, v65, v1, s[4:5] offset:8 sc0
	s_waitcnt vmcnt(0)

; __global__ void __launch_bounds__(NT) fwd_kernel(Params P) {
;     ...
;   for (int ph = P.ph_lo; ph < P.ph_hi; ++ph) {
;     if (ph > P.ph_lo) grid.sync();
.Lxb_c3:
	global_load_dword v2, v0, s[4:5] offset:192 sc1
	global_load_dword v1, v65, s[4:5] offset:8 sc1
	s_waitcnt vmcnt(0)
	v_readfirstlane_b32 s98, v2
	v_readfirstlane_b32 s99, v1
	buffer_inv sc1
	s_waitcnt vmcnt(0)
	s_branch .Lxb_join
.Lxb_fast:
	global_atomic_add v2, v0, v1, s[4:5] offset:128 sc0
	buffer_inv sc1
	s_add_i32 s8, s100, -1
	s_mul_i32 s7, s8, s98
	s_mul_i32 s8, s8, s99
	s_mov_b32 s10, 0
	s_waitcnt vmcnt(0)
	v_readfirstlane_b32 s9, v2
	s_add_i32 s9, s9, 1
	s_cmp_lg_u32 s9, s7
	s_cbranch_scc1 .Lxb_wait
	buffer_wbl2 sc1
	s_waitcnt vmcnt(0)
	global_atomic_add v65, v1, s[4:5]
